# adaLN tile: weight-row loads (global, nt) issued together with the condition-vector loads instead of after their wait (flat loads were capped by lgkmcnt)
# baseline (speedup 1.0000x reference)
.LBB0_139:
	s_ashr_i32 s6, s16, 2
	s_mul_hi_i32 s7, s6, 0x2aaaaaab
	s_lshr_b32 s8, s7, 31
	s_lshr_b32 s7, s7, 3
	s_add_i32 s7, s7, s8
	s_mul_i32 s7, s7, 48
	s_sub_i32 s6, s6, s7
	s_mul_hi_i32 s7, s16, 0x2aaaaaab
	s_lshr_b32 s8, s7, 31
	s_ashr_i32 s14, s7, 5
	s_add_i32 s14, s14, s8
	v_readlane_b32 s36, v241, 18
	s_and_b32 s12, s16, 3
	s_mul_i32 s8, s14, 0xc00000
	v_readlane_b32 s40, v241, 22
	s_mul_hi_i32 s7, s14, 0xc00000
	v_readlane_b32 s41, v241, 23
	s_add_u32 s8, s40, s8
	s_addc_u32 s7, s41, s7
	s_lshl_b32 s9, s12, 8
	v_or_b32_sdwa v2, s9, v1 dst_sel:DWORD dst_unused:UNUSED_PAD src0_sel:DWORD src1_sel:BYTE_0
	v_lshlrev_b32_e32 v128, 2, v2
	v_lshl_add_u64 v[2:3], v[130:131], 0, v[128:129]
	s_barrier
	global_load_dword v4, v[2:3], off
	v_lshl_add_u64 v[2:3], v[132:133], 0, v[128:129]
	global_load_dword v5, v[2:3], off
	v_lshl_add_u64 v[2:3], v[2:3], 0, s[0:1]
	flat_load_dword v6, v[2:3]
	v_lshl_add_u64 v[2:3], v[2:3], 0, s[0:1]
	flat_load_dword v7, v[2:3]
	v_lshl_add_u64 v[2:3], v[2:3], 0, s[0:1]
	flat_load_dword v8, v[2:3]
	v_lshl_add_u64 v[2:3], v[2:3], 0, s[0:1]
	flat_load_dword v9, v[2:3]
	v_lshl_add_u64 v[2:3], v[2:3], 0, s[0:1]
	flat_load_dword v10, v[2:3]
	v_lshl_add_u64 v[2:3], v[2:3], 0, s[0:1]
	flat_load_dword v11, v[2:3]
	v_lshl_add_u64 v[2:3], v[2:3], 0, s[0:1]
	flat_load_dword v12, v[2:3]
	v_lshl_add_u64 v[2:3], v[2:3], 0, s[0:1]
	flat_load_dword v13, v[2:3]
	v_lshl_add_u64 v[2:3], v[2:3], 0, s[0:1]
	flat_load_dword v14, v[2:3]
	v_lshl_add_u64 v[2:3], v[2:3], 0, s[0:1]
	flat_load_dword v15, v[2:3]
	v_lshl_add_u64 v[2:3], v[2:3], 0, s[0:1]
	flat_load_dword v16, v[2:3]
	v_lshl_add_u64 v[2:3], v[2:3], 0, s[0:1]
	flat_load_dword v17, v[2:3]
	v_lshl_add_u64 v[2:3], v[2:3], 0, s[0:1]
	flat_load_dword v18, v[2:3]
	v_lshl_add_u64 v[2:3], v[2:3], 0, s[0:1]
	flat_load_dword v19, v[2:3]
	v_lshl_add_u64 v[2:3], v[2:3], 0, s[0:1]
	flat_load_dword v20, v[2:3]
	v_lshl_add_u64 v[2:3], v[2:3], 0, s[0:1]
	s_add_i32 s9, s9, s17
	s_mul_hi_i32 s13, s9, 0x3000
	s_mulk_i32 s9, 0x3000
	s_add_u32 s15, s8, s9
	s_addc_u32 s13, s7, s13
	s_lshl_b32 s6, s6, 6
	s_ashr_i32 s7, s6, 31
	s_lshl_b64 s[8:9], s[6:7], 2
	s_add_u32 s8, s15, s8
	s_addc_u32 s9, s13, s9
	global_load_dword v179, v134, s[8:9]
	v_readlane_b32 s37, v241, 19
	v_readlane_b32 s38, v241, 20
	v_readlane_b32 s39, v241, 21
	v_readlane_b32 s42, v241, 24
	v_readlane_b32 s43, v241, 25
	v_readlane_b32 s44, v241, 26
	v_readlane_b32 s45, v241, 27
	v_readlane_b32 s46, v241, 28
	v_readlane_b32 s47, v241, 29
	v_readlane_b32 s48, v241, 30
	v_readlane_b32 s49, v241, 31
	v_readlane_b32 s50, v241, 32
	v_readlane_b32 s51, v241, 33
	v_lshl_add_u64 v[254:255], s[8:9], 0, v[134:135]
	v_lshl_add_u64 v[254:255], v[254:255], 0, s[2:3]
	global_load_dword v200, v[254:255], off nt
	v_lshl_add_u64 v[254:255], v[254:255], 0, s[2:3]
	global_load_dword v201, v[254:255], off nt
	v_lshl_add_u64 v[254:255], v[254:255], 0, s[2:3]
	global_load_dword v202, v[254:255], off nt
	v_lshl_add_u64 v[254:255], v[254:255], 0, s[2:3]
	global_load_dword v199, v[254:255], off nt
	v_lshl_add_u64 v[254:255], v[254:255], 0, s[2:3]
	global_load_dword v198, v[254:255], off nt
	v_lshl_add_u64 v[254:255], v[254:255], 0, s[2:3]
	global_load_dword v197, v[254:255], off nt
	v_lshl_add_u64 v[254:255], v[254:255], 0, s[2:3]
	global_load_dword v196, v[254:255], off nt
	v_lshl_add_u64 v[254:255], v[254:255], 0, s[2:3]
	global_load_dword v192, v[254:255], off nt
	v_lshl_add_u64 v[254:255], v[254:255], 0, s[2:3]
	global_load_dword v193, v[254:255], off nt
	v_lshl_add_u64 v[254:255], v[254:255], 0, s[2:3]
	global_load_dword v194, v[254:255], off nt
	v_lshl_add_u64 v[254:255], v[254:255], 0, s[2:3]
	global_load_dword v195, v[254:255], off nt
	v_lshl_add_u64 v[254:255], v[254:255], 0, s[2:3]
	global_load_dword v191, v[254:255], off nt
	v_lshl_add_u64 v[254:255], v[254:255], 0, s[2:3]
	global_load_dword v190, v[254:255], off nt
	v_lshl_add_u64 v[254:255], v[254:255], 0, s[2:3]
	global_load_dword v189, v[254:255], off nt
	v_lshl_add_u64 v[254:255], v[254:255], 0, s[2:3]
	global_load_dword v188, v[254:255], off nt
	v_lshl_add_u64 v[254:255], v[254:255], 0, s[2:3]
	global_load_dword v184, v[254:255], off nt
	v_lshl_add_u64 v[254:255], v[254:255], 0, s[2:3]
	global_load_dword v185, v[254:255], off nt
	v_lshl_add_u64 v[254:255], v[254:255], 0, s[2:3]
	global_load_dword v186, v[254:255], off nt
	v_lshl_add_u64 v[254:255], v[254:255], 0, s[2:3]
	global_load_dword v187, v[254:255], off nt
	v_lshl_add_u64 v[254:255], v[254:255], 0, s[2:3]
	global_load_dword v183, v[254:255], off nt
	v_lshl_add_u64 v[254:255], v[254:255], 0, s[2:3]
	global_load_dword v182, v[254:255], off nt
	v_lshl_add_u64 v[254:255], v[254:255], 0, s[2:3]
	global_load_dword v181, v[254:255], off nt
	v_lshl_add_u64 v[254:255], v[254:255], 0, s[2:3]
	global_load_dword v180, v[254:255], off nt
	v_lshl_add_u64 v[254:255], v[254:255], 0, s[2:3]
	global_load_dword v143, v[254:255], off nt
	v_lshl_add_u64 v[254:255], v[254:255], 0, s[2:3]
	global_load_dword v144, v[254:255], off nt
	v_lshl_add_u64 v[254:255], v[254:255], 0, s[2:3]
	global_load_dword v145, v[254:255], off nt
	v_lshl_add_u64 v[254:255], v[254:255], 0, s[2:3]
	global_load_dword v146, v[254:255], off nt
	v_lshl_add_u64 v[254:255], v[254:255], 0, s[2:3]
	global_load_dword v142, v[254:255], off nt
	v_lshl_add_u64 v[254:255], v[254:255], 0, s[2:3]
	global_load_dword v141, v[254:255], off nt
	v_lshl_add_u64 v[254:255], v[254:255], 0, s[2:3]
	global_load_dword v140, v[254:255], off nt
	v_lshl_add_u64 v[254:255], v[254:255], 0, s[2:3]
	global_load_dword v128, v[254:255], off nt
	v_lshl_add_u64 v[254:255], v[254:255], 0, s[2:3]
	s_waitcnt vmcnt(0)
	v_mul_f32_e32 v2, 0xbfb8aa3b, v4
	v_exp_f32_e32 v2, v2
	v_mul_f32_e32 v3, 0xbfb8aa3b, v5
	v_exp_f32_e32 v3, v3
	v_add_f32_e32 v2, 1.0, v2
	v_rcp_f32_e32 v2, v2
	s_waitcnt lgkmcnt(0)
	v_mul_f32_e32 v21, 0xbfb8aa3b, v6
	v_mul_f32_e32 v22, 0xbfb8aa3b, v7
	v_exp_f32_e32 v22, v22
	v_add_f32_e32 v3, 1.0, v3
	v_exp_f32_e32 v21, v21
	v_rcp_f32_e32 v3, v3
	v_add_f32_e32 v22, 1.0, v22
	v_mul_f32_e32 v2, v4, v2
	v_rcp_f32_e32 v4, v22
	v_add_f32_e32 v21, 1.0, v21
	v_mul_f32_e32 v3, v5, v3
	v_mul_f32_e32 v23, 0xbfb8aa3b, v8
	v_rcp_f32_e32 v21, v21
	ds_write2st64_b32 v127, v2, v3 offset1:8
	v_mul_f32_e32 v3, v7, v4
	v_mul_f32_e32 v4, 0xbfb8aa3b, v9
	v_exp_f32_e32 v23, v23
	v_exp_f32_e32 v4, v4
	v_mul_f32_e32 v2, v6, v21
	ds_write2st64_b32 v127, v2, v3 offset0:16 offset1:24
	v_add_f32_e32 v2, 1.0, v23
	v_add_f32_e32 v3, 1.0, v4
	v_rcp_f32_e32 v2, v2
	v_rcp_f32_e32 v3, v3
	v_mul_f32_e32 v4, 0xbfb8aa3b, v10
	v_exp_f32_e32 v4, v4
	v_mul_f32_e32 v2, v8, v2
	v_mul_f32_e32 v3, v9, v3
	ds_write2st64_b32 v127, v2, v3 offset0:32 offset1:40
	v_mul_f32_e32 v3, 0xbfb8aa3b, v11
	v_add_f32_e32 v2, 1.0, v4
	v_exp_f32_e32 v3, v3
	v_mul_f32_e32 v4, 0xbfb8aa3b, v12
	v_exp_f32_e32 v4, v4
	v_rcp_f32_e32 v2, v2
	v_add_f32_e32 v3, 1.0, v3
	v_rcp_f32_e32 v3, v3
	v_add_f32_e32 v4, 1.0, v4
	v_mul_f32_e32 v5, 0xbfb8aa3b, v13
	v_rcp_f32_e32 v4, v4
	v_exp_f32_e32 v5, v5
	v_mul_f32_e32 v2, v10, v2
	v_mul_f32_e32 v3, v11, v3
	ds_write2st64_b32 v127, v2, v3 offset0:48 offset1:56
	v_mul_f32_e32 v2, v12, v4
	v_add_f32_e32 v3, 1.0, v5
	v_mul_f32_e32 v4, 0xbfb8aa3b, v14
	v_mul_f32_e32 v5, 0xbfb8aa3b, v15
	v_exp_f32_e32 v4, v4
	v_exp_f32_e32 v5, v5
	v_rcp_f32_e32 v3, v3
	v_add_f32_e32 v4, 1.0, v4
	v_add_f32_e32 v5, 1.0, v5
	v_rcp_f32_e32 v4, v4
	v_rcp_f32_e32 v5, v5
	v_mul_f32_e32 v3, v13, v3
	ds_write2st64_b32 v127, v2, v3 offset0:64 offset1:72
	v_mul_f32_e32 v2, v14, v4
	v_mul_f32_e32 v3, v15, v5
	v_mul_f32_e32 v4, 0xbfb8aa3b, v16
	v_mul_f32_e32 v5, 0xbfb8aa3b, v17
	v_exp_f32_e32 v4, v4
	v_exp_f32_e32 v5, v5
	ds_write2st64_b32 v127, v2, v3 offset0:80 offset1:88
	v_add_f32_e32 v2, 1.0, v4
	v_add_f32_e32 v3, 1.0, v5
	v_rcp_f32_e32 v2, v2
	v_rcp_f32_e32 v3, v3
	v_mul_f32_e32 v4, 0xbfb8aa3b, v18
	v_exp_f32_e32 v4, v4
	v_mul_f32_e32 v2, v16, v2
	v_mul_f32_e32 v3, v17, v3
	ds_write2st64_b32 v127, v2, v3 offset0:96 offset1:104
	v_mul_f32_e32 v3, 0xbfb8aa3b, v19
	v_add_f32_e32 v2, 1.0, v4
	v_exp_f32_e32 v3, v3
	v_mul_f32_e32 v4, 0xbfb8aa3b, v20
	v_exp_f32_e32 v4, v4
	v_rcp_f32_e32 v2, v2
	v_add_f32_e32 v3, 1.0, v3
	v_rcp_f32_e32 v3, v3
	v_add_f32_e32 v4, 1.0, v4
	v_rcp_f32_e32 v4, v4
	v_mul_f32_e32 v2, v18, v2
	v_mul_f32_e32 v3, v19, v3
	ds_write2st64_b32 v127, v2, v3 offset0:112 offset1:120
	v_mul_f32_e32 v2, v20, v4
	ds_write_b32 v127, v2 offset:32768
	s_waitcnt lgkmcnt(0)
	s_barrier
	ds_read_b128 v[14:17], v137
	ds_read_b128 v[10:13], v137 offset:1024
	ds_read_b128 v[2:5], v137 offset:16
	ds_read_b128 v[6:9], v137 offset:2048
	ds_read_b128 v[26:29], v137 offset:1040
	ds_read_b128 v[18:21], v137 offset:3072
	ds_read_b128 v[30:33], v137 offset:2064
	ds_read_b128 v[22:25], v137 offset:4096
	ds_read_b128 v[34:37], v137 offset:3088
	ds_read_b128 v[74:77], v137 offset:5120
	ds_read_b128 v[38:41], v137 offset:4112
	ds_read_b128 v[78:81], v137 offset:6144
	ds_read_b128 v[42:45], v137 offset:5136
	ds_read_b128 v[82:85], v137 offset:7168
	ds_read_b128 v[46:49], v137 offset:6160
	ds_read_b128 v[86:89], v137 offset:8192
	ds_read_b128 v[50:53], v137 offset:7184
	ds_read_b128 v[90:93], v137 offset:9216
	ds_read_b128 v[54:57], v137 offset:8208
	ds_read_b128 v[94:97], v137 offset:10240
	ds_read_b128 v[58:61], v137 offset:9232
	s_waitcnt lgkmcnt(0)
	v_fma_f32 v148, v179, v6, 0
	v_fma_f32 v153, v179, v82, 0
	ds_read_b128 v[98:101], v137 offset:11264
	ds_read_b128 v[102:105], v137 offset:12288
	ds_read_b128 v[62:65], v137 offset:10256
	v_fma_f32 v139, v179, v14, 0
	v_fma_f32 v147, v179, v10, 0
	v_fma_f32 v149, v179, v18, 0
	v_fma_f32 v150, v179, v22, 0
	v_fma_f32 v156, v179, v94, 0
	s_waitcnt vmcnt(0)
	v_fmac_f32_e32 v148, v200, v7
	v_fmac_f32_e32 v153, v200, v83
	v_fmac_f32_e32 v139, v200, v15
	v_fmac_f32_e32 v147, v200, v11
	v_fmac_f32_e32 v148, v201, v8
	v_fmac_f32_e32 v149, v200, v19
	v_fmac_f32_e32 v150, v200, v23
	v_fmac_f32_e32 v153, v201, v84
	v_fmac_f32_e32 v156, v200, v95
	ds_read_b128 v[66:69], v137 offset:11280
	ds_read_b128 v[70:73], v137 offset:12304
	s_waitcnt lgkmcnt(4)
	v_fma_f32 v157, v179, v98, 0
	v_fmac_f32_e32 v139, v201, v16
	v_fmac_f32_e32 v147, v201, v12
	v_fmac_f32_e32 v148, v202, v9
	ds_read_b128 v[106:109], v137 offset:13312
	ds_read_b128 v[6:9], v137 offset:13328
	v_fmac_f32_e32 v149, v201, v20
	v_fmac_f32_e32 v150, v201, v24
	v_fmac_f32_e32 v153, v202, v85
	ds_read_b128 v[82:85], v137 offset:16384
	v_fmac_f32_e32 v156, v201, v96
	v_fmac_f32_e32 v139, v202, v17
	v_fmac_f32_e32 v147, v202, v13
	v_fmac_f32_e32 v149, v202, v21
	v_fmac_f32_e32 v150, v202, v25
	ds_read_b128 v[110:113], v137 offset:14336
	ds_read_b128 v[14:17], v137 offset:14352
	ds_read_b128 v[114:117], v137 offset:15360
	ds_read_b128 v[10:13], v137 offset:15376
	ds_read_b128 v[18:21], v137 offset:16400
	v_fmac_f32_e32 v156, v202, v97
	v_fmac_f32_e32 v157, v200, v99
	ds_read_b128 v[94:97], v137 offset:17408
	ds_read_b128 v[22:25], v137 offset:17424
	v_fma_f32 v154, v179, v86, 0
	v_fma_f32 v155, v179, v90, 0
	v_fmac_f32_e32 v157, v201, v100
	v_fmac_f32_e32 v154, v200, v87
	v_fmac_f32_e32 v155, v200, v91
	v_fmac_f32_e32 v157, v202, v101
	ds_read_b128 v[98:101], v137 offset:20480
	v_fmac_f32_e32 v154, v201, v88
	v_fmac_f32_e32 v155, v201, v92
	s_waitcnt lgkmcnt(14)
	v_fma_f32 v158, v179, v102, 0
	v_fmac_f32_e32 v154, v202, v89
	v_fmac_f32_e32 v155, v202, v93
	s_waitcnt lgkmcnt(8)
	v_fma_f32 v162, v179, v82, 0
	ds_read_b128 v[86:89], v137 offset:18432
	ds_read_b128 v[90:93], v137 offset:19456
	s_waitcnt lgkmcnt(4)
	v_fma_f32 v163, v179, v94, 0
	v_fmac_f32_e32 v158, v200, v103
	v_fmac_f32_e32 v162, v200, v83
	v_fmac_f32_e32 v163, v200, v95
	v_fma_f32 v151, v179, v74, 0
	v_fma_f32 v152, v179, v78, 0
	v_fmac_f32_e32 v158, v201, v104
	v_fmac_f32_e32 v162, v201, v84
	v_fmac_f32_e32 v163, v201, v96
	v_fmac_f32_e32 v151, v200, v75
	v_fmac_f32_e32 v152, v200, v79
	v_fmac_f32_e32 v158, v202, v105
	v_fmac_f32_e32 v162, v202, v85
	v_fmac_f32_e32 v163, v202, v97
	ds_read_b128 v[82:85], v137 offset:20496
	s_waitcnt lgkmcnt(3)
	v_fma_f32 v166, v179, v98, 0
	ds_read_b128 v[94:97], v137 offset:21504
	ds_read_b128 v[102:105], v137 offset:22528
	v_fmac_f32_e32 v151, v201, v76
	v_fmac_f32_e32 v152, v201, v80
	v_fmac_f32_e32 v166, v200, v99
	v_fmac_f32_e32 v151, v202, v77
	v_fmac_f32_e32 v152, v202, v81
	ds_read_b128 v[74:77], v137 offset:18448
	s_waitcnt lgkmcnt(5)
	v_fma_f32 v164, v179, v86, 0
	ds_read_b128 v[78:81], v137 offset:19472
	s_waitcnt lgkmcnt(5)
	v_fma_f32 v165, v179, v90, 0
	v_fmac_f32_e32 v166, v201, v100
	v_fmac_f32_e32 v164, v200, v87
	v_fmac_f32_e32 v165, v200, v91
	v_fmac_f32_e32 v166, v202, v101
	ds_read_b128 v[98:101], v137 offset:23552
	v_fmac_f32_e32 v164, v201, v88
	v_fmac_f32_e32 v165, v201, v92
	v_fmac_f32_e32 v164, v202, v89
	v_fmac_f32_e32 v165, v202, v93
	ds_read_b128 v[86:89], v137 offset:21520
	s_waitcnt lgkmcnt(5)
	v_fma_f32 v167, v179, v94, 0
	ds_read_b128 v[90:93], v137 offset:22544
	s_waitcnt lgkmcnt(5)
	v_fma_f32 v168, v179, v102, 0
	v_fmac_f32_e32 v167, v200, v95
	v_fmac_f32_e32 v168, v200, v103
	v_fmac_f32_e32 v167, v201, v96
	v_fmac_f32_e32 v168, v201, v104
	v_fma_f32 v159, v179, v106, 0
	v_fmac_f32_e32 v167, v202, v97
	v_fmac_f32_e32 v168, v202, v105
	ds_read_b128 v[102:105], v137 offset:24576
	ds_read_b128 v[94:97], v137 offset:23568
	s_waitcnt lgkmcnt(4)
	v_fma_f32 v169, v179, v98, 0
	v_fmac_f32_e32 v159, v200, v107
	v_fmac_f32_e32 v169, v200, v99
	v_fmac_f32_e32 v159, v201, v108
	v_fmac_f32_e32 v169, v201, v100
	v_fmac_f32_e32 v159, v202, v109
	v_fmac_f32_e32 v169, v202, v101
	ds_read_b128 v[98:101], v137 offset:24592
	ds_read_b128 v[106:109], v137 offset:25600
	v_fma_f32 v160, v179, v110, 0
	s_waitcnt lgkmcnt(3)
	v_fma_f32 v170, v179, v102, 0
	v_fmac_f32_e32 v160, v200, v111
	v_fmac_f32_e32 v170, v200, v103
	v_fmac_f32_e32 v160, v201, v112
	v_fmac_f32_e32 v170, v201, v104
	v_fmac_f32_e32 v160, v202, v113
	v_fmac_f32_e32 v170, v202, v105
	ds_read_b128 v[110:113], v137 offset:26624
	ds_read_b128 v[102:105], v137 offset:25616
	v_fma_f32 v161, v179, v114, 0
	s_waitcnt lgkmcnt(2)
	v_fma_f32 v171, v179, v106, 0
	v_fmac_f32_e32 v161, v200, v115
	v_fmac_f32_e32 v171, v200, v107
	v_fmac_f32_e32 v161, v201, v116
	v_fmac_f32_e32 v171, v201, v108
	v_fmac_f32_e32 v161, v202, v117
	v_fmac_f32_e32 v171, v202, v109
	ds_read_b128 v[106:109], v137 offset:26640
	ds_read_b128 v[114:117], v137 offset:27648
	s_waitcnt lgkmcnt(3)
	v_fma_f32 v172, v179, v110, 0
	v_fmac_f32_e32 v172, v200, v111
	v_fmac_f32_e32 v172, v201, v112
	v_fmac_f32_e32 v172, v202, v113
	ds_read_b128 v[118:121], v137 offset:28672
	ds_read_b128 v[110:113], v137 offset:27664
	s_waitcnt lgkmcnt(2)
	v_fma_f32 v173, v179, v114, 0
	v_fmac_f32_e32 v173, v200, v115
	v_fmac_f32_e32 v173, v201, v116
	s_waitcnt lgkmcnt(1)
	v_fma_f32 v174, v179, v118, 0
	v_fmac_f32_e32 v173, v202, v117
	ds_read_b128 v[114:117], v137 offset:28688
	ds_read_b128 v[122:125], v137 offset:29696
	v_fmac_f32_e32 v174, v200, v119
	v_fmac_f32_e32 v174, v201, v120
	v_fmac_f32_e32 v174, v202, v121
	ds_read_b128 v[204:207], v137 offset:30720
	ds_read_b128 v[118:121], v137 offset:29712
	s_waitcnt lgkmcnt(2)
	v_fma_f32 v175, v179, v122, 0
	v_fmac_f32_e32 v175, v200, v123
	v_fmac_f32_e32 v175, v201, v124
	s_waitcnt lgkmcnt(1)
	v_fma_f32 v176, v179, v204, 0
	v_fmac_f32_e32 v176, v200, v205
	v_fmac_f32_e32 v175, v202, v125
	ds_read_b128 v[122:125], v137 offset:30736
	ds_read_b128 v[208:211], v137 offset:31744
	v_fmac_f32_e32 v176, v201, v206
	v_fmac_f32_e32 v176, v202, v207
	ds_read_b128 v[204:207], v137 offset:32768
	ds_read_b128 v[212:215], v137 offset:31760
	v_fmac_f32_e32 v139, v199, v2
	s_waitcnt lgkmcnt(2)
	v_fma_f32 v177, v179, v208, 0
	v_fmac_f32_e32 v147, v199, v26
	s_waitcnt lgkmcnt(1)
	v_fma_f32 v178, v179, v204, 0
	v_fmac_f32_e32 v148, v199, v30
	v_fmac_f32_e32 v149, v199, v34
	v_fmac_f32_e32 v150, v199, v38
	v_fmac_f32_e32 v151, v199, v42
	v_fmac_f32_e32 v152, v199, v46
	v_fmac_f32_e32 v153, v199, v50
	v_fmac_f32_e32 v157, v199, v66
	v_fmac_f32_e32 v158, v199, v70
	v_fmac_f32_e32 v159, v199, v6
	v_fmac_f32_e32 v160, v199, v14
	v_fmac_f32_e32 v161, v199, v10
	v_fmac_f32_e32 v162, v199, v18
	v_fmac_f32_e32 v163, v199, v22
	v_fmac_f32_e32 v164, v199, v74
	v_fmac_f32_e32 v165, v199, v78
	v_fmac_f32_e32 v177, v200, v209
	v_fmac_f32_e32 v178, v200, v205
	v_fmac_f32_e32 v139, v198, v3
	v_fmac_f32_e32 v147, v198, v27
	v_fmac_f32_e32 v148, v198, v31
	v_fmac_f32_e32 v149, v198, v35
	v_fmac_f32_e32 v150, v198, v39
	v_fmac_f32_e32 v151, v198, v43
	v_fmac_f32_e32 v152, v198, v47
	v_fmac_f32_e32 v153, v198, v51
	v_fmac_f32_e32 v157, v198, v67
	v_fmac_f32_e32 v158, v198, v71
	v_fmac_f32_e32 v159, v198, v7
	v_fmac_f32_e32 v160, v198, v15
	v_fmac_f32_e32 v161, v198, v11
	v_fmac_f32_e32 v162, v198, v19
	v_fmac_f32_e32 v163, v198, v23
	v_fmac_f32_e32 v164, v198, v75
	v_fmac_f32_e32 v165, v198, v79
	v_fmac_f32_e32 v177, v201, v210
	v_fmac_f32_e32 v178, v201, v206
	v_fmac_f32_e32 v139, v197, v4
	v_fmac_f32_e32 v147, v197, v28
	v_fmac_f32_e32 v148, v197, v32
	v_fmac_f32_e32 v149, v197, v36
	v_fmac_f32_e32 v150, v197, v40
	v_fmac_f32_e32 v151, v197, v44
	v_fmac_f32_e32 v152, v197, v48
	v_fmac_f32_e32 v153, v197, v52
	v_fmac_f32_e32 v154, v199, v54
	v_fmac_f32_e32 v157, v197, v68
	v_fmac_f32_e32 v158, v197, v72
	v_fmac_f32_e32 v166, v199, v82
	v_fmac_f32_e32 v167, v199, v86
	v_fmac_f32_e32 v168, v199, v90
	v_fmac_f32_e32 v159, v197, v8
	v_fmac_f32_e32 v160, v197, v16
	v_fmac_f32_e32 v161, v197, v12
	v_fmac_f32_e32 v162, v197, v20
	v_fmac_f32_e32 v163, v197, v24
	v_fmac_f32_e32 v164, v197, v76
	v_fmac_f32_e32 v165, v197, v80
	v_fmac_f32_e32 v177, v202, v211
	ds_read_b128 v[208:211], v137 offset:32784
	ds_read_b128 v[216:219], v137 offset:33792
	v_fmac_f32_e32 v178, v202, v207
	ds_read_b128 v[204:207], v137 offset:33808
	v_fmac_f32_e32 v139, v196, v5
	v_fmac_f32_e32 v147, v196, v29
	v_fmac_f32_e32 v148, v196, v33
	v_fmac_f32_e32 v149, v196, v37
	v_fmac_f32_e32 v150, v196, v41
	v_fmac_f32_e32 v151, v196, v45
	v_fmac_f32_e32 v152, v196, v49
	v_fmac_f32_e32 v153, v196, v53
	v_fmac_f32_e32 v154, v198, v55
	v_fmac_f32_e32 v157, v196, v69
	v_fmac_f32_e32 v158, v196, v73
	v_fmac_f32_e32 v166, v198, v83
	v_fmac_f32_e32 v167, v198, v87
	v_fmac_f32_e32 v168, v198, v91
	v_fmac_f32_e32 v159, v196, v9
	v_fmac_f32_e32 v160, v196, v17
	ds_read_b128 v[6:9], v137 offset:32
	ds_read_b128 v[2:5], v137 offset:48
	v_fmac_f32_e32 v161, v196, v13
	v_fmac_f32_e32 v162, v196, v21
	v_fmac_f32_e32 v163, v196, v25
	v_fmac_f32_e32 v164, v196, v77
	v_fmac_f32_e32 v165, v196, v81
	ds_read_b128 v[10:13], v137 offset:1056
	ds_read_b128 v[14:17], v137 offset:2080
	ds_read_b128 v[22:25], v137 offset:1072
	ds_read_b128 v[18:21], v137 offset:3104
	ds_read_b128 v[26:29], v137 offset:2096
	ds_read_b128 v[46:49], v137 offset:4128
	ds_read_b128 v[30:33], v137 offset:3120
	ds_read_b128 v[66:69], v137 offset:5152
	ds_read_b128 v[34:37], v137 offset:4144
	ds_read_b128 v[70:73], v137 offset:6176
	ds_read_b128 v[38:41], v137 offset:5168
	ds_read_b128 v[74:77], v137 offset:7200
	ds_read_b128 v[42:45], v137 offset:6192
	ds_read_b128 v[78:81], v137 offset:8224
	ds_read_b128 v[50:53], v137 offset:7216
	v_fmac_f32_e32 v154, v197, v56
	v_fmac_f32_e32 v166, v197, v84
	v_fmac_f32_e32 v167, v197, v88
	v_fmac_f32_e32 v168, v197, v92
	v_fmac_f32_e32 v154, v196, v57
	v_fmac_f32_e32 v166, v196, v85
	v_fmac_f32_e32 v167, v196, v89
	v_fmac_f32_e32 v168, v196, v93
	ds_read_b128 v[82:85], v137 offset:9248
	ds_read_b128 v[86:89], v137 offset:10272
	ds_read_b128 v[54:57], v137 offset:8240
	ds_read_b128 v[90:93], v137 offset:11296
	s_waitcnt lgkmcnt(14)
	v_fmac_f32_e32 v139, v192, v6
	s_waitcnt lgkmcnt(5)
	v_fmac_f32_e32 v154, v192, v78
	v_fmac_f32_e32 v169, v199, v94
	v_fmac_f32_e32 v139, v193, v7
	v_fmac_f32_e32 v154, v193, v79
	v_fmac_f32_e32 v155, v199, v58
	v_fmac_f32_e32 v169, v198, v95
	v_fmac_f32_e32 v139, v194, v8
	v_fmac_f32_e32 v154, v194, v80
	v_fmac_f32_e32 v155, v198, v59
	v_fmac_f32_e32 v169, v197, v96
	v_fmac_f32_e32 v152, v192, v70
	v_fmac_f32_e32 v139, v195, v9
	ds_read_b128 v[6:9], v137 offset:11312
	s_waitcnt lgkmcnt(1)
	v_fmac_f32_e32 v157, v192, v90
	v_fmac_f32_e32 v154, v195, v81
	ds_read_b128 v[78:81], v137 offset:16416
	v_fmac_f32_e32 v155, v197, v60
	v_fmac_f32_e32 v169, v196, v97
	ds_read_b128 v[94:97], v137 offset:12320
	v_fmac_f32_e32 v152, v193, v71
	v_fmac_f32_e32 v157, v193, v91
	v_fmac_f32_e32 v155, v196, v61
	v_fmac_f32_e32 v156, v199, v62
	v_fmac_f32_e32 v151, v192, v66
	v_fmac_f32_e32 v152, v194, v72
	v_fmac_f32_e32 v157, v194, v92
	v_fmac_f32_e32 v156, v198, v63
	v_fmac_f32_e32 v147, v192, v10
	v_fmac_f32_e32 v153, v192, v74
	v_fmac_f32_e32 v155, v192, v82
	v_fmac_f32_e32 v151, v193, v67
	v_fmac_f32_e32 v152, v195, v73
	ds_read_b128 v[70:73], v137 offset:14368
	v_fmac_f32_e32 v157, v195, v93
	ds_read_b128 v[90:93], v137 offset:19488
	v_fmac_f32_e32 v156, v197, v64
	v_fmac_f32_e32 v147, v193, v11
	v_fmac_f32_e32 v151, v194, v68
	v_fmac_f32_e32 v153, v193, v75
	v_fmac_f32_e32 v155, v193, v83
	v_fmac_f32_e32 v156, v196, v65
	v_fmac_f32_e32 v149, v192, v18
	v_fmac_f32_e32 v147, v194, v12
	v_fmac_f32_e32 v151, v195, v69
	v_fmac_f32_e32 v153, v194, v76
	v_fmac_f32_e32 v155, v194, v84
	ds_read_b128 v[66:69], v137 offset:16432
	s_waitcnt lgkmcnt(4)
	v_fmac_f32_e32 v162, v192, v78
	v_fmac_f32_e32 v156, v192, v86
	v_fmac_f32_e32 v147, v195, v13
	v_fmac_f32_e32 v149, v193, v19
	ds_read_b128 v[10:13], v137 offset:12336
	s_waitcnt lgkmcnt(4)
	v_fmac_f32_e32 v158, v192, v94
	v_fmac_f32_e32 v153, v195, v77
	v_fmac_f32_e32 v155, v195, v85
	ds_read_b128 v[74:77], v137 offset:15392
	ds_read_b128 v[82:85], v137 offset:17440
	v_fmac_f32_e32 v162, v193, v79
	v_fmac_f32_e32 v149, v194, v20
	v_fmac_f32_e32 v156, v193, v87
	v_fmac_f32_e32 v158, v193, v95
	v_fmac_f32_e32 v162, v194, v80
	v_fmac_f32_e32 v170, v199, v98
	v_fmac_f32_e32 v150, v192, v46
	v_fmac_f32_e32 v149, v195, v21
	ds_read_b128 v[18:21], v137 offset:14384
	s_waitcnt lgkmcnt(6)
	v_fmac_f32_e32 v160, v192, v70
	v_fmac_f32_e32 v156, v194, v88
	v_fmac_f32_e32 v158, v194, v96
	v_fmac_f32_e32 v162, v195, v81
	ds_read_b128 v[78:81], v137 offset:19504
	s_waitcnt lgkmcnt(6)
	v_fmac_f32_e32 v165, v192, v90
	v_fmac_f32_e32 v170, v198, v99
	v_fmac_f32_e32 v150, v193, v47
	v_fmac_f32_e32 v156, v195, v89
	v_fmac_f32_e32 v158, v195, v97
	v_fmac_f32_e32 v160, v193, v71
	ds_read_b128 v[86:89], v137 offset:18464
	ds_read_b128 v[94:97], v137 offset:20512
	v_fmac_f32_e32 v165, v193, v91
	v_fmac_f32_e32 v170, v197, v100
	v_fmac_f32_e32 v150, v194, v48
	v_fmac_f32_e32 v160, v194, v72
	v_fmac_f32_e32 v165, v194, v92
	v_fmac_f32_e32 v170, v196, v101
	v_fmac_f32_e32 v150, v195, v49
	ds_read_b128 v[98:101], v137 offset:13344
	ds_read_b128 v[46:49], v137 offset:15408
	s_waitcnt lgkmcnt(7)
	v_fmac_f32_e32 v161, v192, v74
	v_fmac_f32_e32 v160, v195, v73
	ds_read_b128 v[70:73], v137 offset:17456
	s_waitcnt lgkmcnt(7)
	v_fmac_f32_e32 v163, v192, v82
	v_fmac_f32_e32 v165, v195, v93
	ds_read_b128 v[90:93], v137 offset:21536
	v_fmac_f32_e32 v161, v193, v75
	v_fmac_f32_e32 v163, v193, v83
	v_fmac_f32_e32 v148, v192, v14
	v_fmac_f32_e32 v161, v194, v76
	v_fmac_f32_e32 v163, v194, v84
	v_fmac_f32_e32 v148, v193, v15
	v_fmac_f32_e32 v161, v195, v77
	ds_read_b128 v[74:77], v137 offset:18480
	s_waitcnt lgkmcnt(6)
	v_fmac_f32_e32 v164, v192, v86
	v_fmac_f32_e32 v163, v195, v85
	ds_read_b128 v[82:85], v137 offset:20528
	s_waitcnt lgkmcnt(6)
	v_fmac_f32_e32 v166, v192, v94
	v_fmac_f32_e32 v148, v194, v16
	v_fmac_f32_e32 v164, v193, v87
	v_fmac_f32_e32 v166, v193, v95
	v_fmac_f32_e32 v148, v195, v17
	ds_read_b128 v[14:17], v137 offset:13360
	s_waitcnt lgkmcnt(6)
	v_fmac_f32_e32 v159, v192, v98
	v_fmac_f32_e32 v164, v194, v88
	v_fmac_f32_e32 v166, v194, v96
	s_waitcnt lgkmcnt(3)
	v_fmac_f32_e32 v167, v192, v90
	ds_read_b128 v[58:61], v137 offset:9264
	ds_read_b128 v[62:65], v137 offset:10288
	v_fmac_f32_e32 v159, v193, v99
	v_fmac_f32_e32 v164, v195, v89
	v_fmac_f32_e32 v166, v195, v97
	ds_read_b128 v[94:97], v137 offset:22560
	ds_read_b128 v[86:89], v137 offset:21552
	v_fmac_f32_e32 v167, v193, v91
	v_fmac_f32_e32 v159, v194, v100
	v_fmac_f32_e32 v167, v194, v92
	v_fmac_f32_e32 v159, v195, v101
	v_fmac_f32_e32 v167, v195, v93
	ds_read_b128 v[90:93], v137 offset:22576
	ds_read_b128 v[98:101], v137 offset:23584
	v_fmac_f32_e32 v171, v199, v102
	s_waitcnt lgkmcnt(3)
	v_fmac_f32_e32 v168, v192, v94
	v_fmac_f32_e32 v171, v198, v103
	v_fmac_f32_e32 v168, v193, v95
	v_fmac_f32_e32 v171, v197, v104
	v_fmac_f32_e32 v168, v194, v96
	v_fmac_f32_e32 v172, v199, v106
	v_fmac_f32_e32 v171, v196, v105
	v_fmac_f32_e32 v168, v195, v97
	ds_read_b128 v[102:105], v137 offset:24608
	ds_read_b128 v[94:97], v137 offset:23600
	s_waitcnt lgkmcnt(2)
	v_fmac_f32_e32 v169, v192, v98
	v_fmac_f32_e32 v172, v198, v107
	v_fmac_f32_e32 v169, v193, v99
	v_fmac_f32_e32 v172, v197, v108
	v_fmac_f32_e32 v169, v194, v100
	v_fmac_f32_e32 v172, v196, v109
	v_fmac_f32_e32 v169, v195, v101
	ds_read_b128 v[98:101], v137 offset:24624
	ds_read_b128 v[106:109], v137 offset:25632
	v_fmac_f32_e32 v173, v199, v110
	s_waitcnt lgkmcnt(3)
	v_fmac_f32_e32 v170, v192, v102
	v_fmac_f32_e32 v173, v198, v111
	v_fmac_f32_e32 v170, v193, v103
	v_fmac_f32_e32 v173, v197, v112
	v_fmac_f32_e32 v170, v194, v104
	v_fmac_f32_e32 v173, v196, v113
	v_fmac_f32_e32 v170, v195, v105
	ds_read_b128 v[110:113], v137 offset:26656
	ds_read_b128 v[102:105], v137 offset:25648
	v_fmac_f32_e32 v174, v199, v114
	s_waitcnt lgkmcnt(2)
	v_fmac_f32_e32 v171, v192, v106
	v_fmac_f32_e32 v174, v198, v115
	v_fmac_f32_e32 v171, v193, v107
	v_fmac_f32_e32 v174, v197, v116
	v_fmac_f32_e32 v171, v194, v108
	v_fmac_f32_e32 v175, v199, v118
	v_fmac_f32_e32 v174, v196, v117
	v_fmac_f32_e32 v171, v195, v109
	ds_read_b128 v[106:109], v137 offset:26672
	ds_read_b128 v[114:117], v137 offset:27680
	s_waitcnt lgkmcnt(3)
	v_fmac_f32_e32 v172, v192, v110
	v_fmac_f32_e32 v175, v198, v119
	v_fmac_f32_e32 v172, v193, v111
	v_fmac_f32_e32 v175, v197, v120
	v_fmac_f32_e32 v172, v194, v112
	v_fma_f32 v179, v179, v216, 0
	v_fmac_f32_e32 v175, v196, v121
	v_fmac_f32_e32 v172, v195, v113
	ds_read_b128 v[118:121], v137 offset:28704
	ds_read_b128 v[110:113], v137 offset:27696
	v_fmac_f32_e32 v179, v200, v217
	v_fmac_f32_e32 v179, v201, v218
	v_fmac_f32_e32 v176, v199, v122
	s_waitcnt lgkmcnt(2)
	v_fmac_f32_e32 v173, v192, v114
	v_fmac_f32_e32 v179, v202, v219
	v_fmac_f32_e32 v176, v198, v123
	v_fmac_f32_e32 v173, v193, v115
	v_fmac_f32_e32 v177, v199, v212
	v_fmac_f32_e32 v178, v199, v208
	v_fmac_f32_e32 v179, v199, v204
	v_fmac_f32_e32 v176, v197, v124
	v_fmac_f32_e32 v173, v194, v116
	s_waitcnt lgkmcnt(1)
	v_fmac_f32_e32 v174, v192, v118
	v_fmac_f32_e32 v177, v198, v213
	v_fmac_f32_e32 v178, v198, v209
	v_fmac_f32_e32 v179, v198, v205
	v_fmac_f32_e32 v176, v196, v125
	v_fmac_f32_e32 v173, v195, v117
	ds_read_b128 v[114:117], v137 offset:28720
	ds_read_b128 v[122:125], v137 offset:29728
	v_fmac_f32_e32 v174, v193, v119
	v_fmac_f32_e32 v177, v197, v214
	v_fmac_f32_e32 v178, v197, v210
	v_fmac_f32_e32 v179, v197, v206
	v_fmac_f32_e32 v174, v194, v120
	v_fmac_f32_e32 v177, v196, v215
	v_fmac_f32_e32 v178, v196, v211
	v_fmac_f32_e32 v179, v196, v207
	v_fmac_f32_e32 v174, v195, v121
	ds_read_b128 v[196:199], v137 offset:30752
	ds_read_b128 v[118:121], v137 offset:29744
	s_waitcnt lgkmcnt(2)
	v_fmac_f32_e32 v175, v192, v122
	v_fmac_f32_e32 v175, v193, v123
	v_fmac_f32_e32 v175, v194, v124
	s_waitcnt lgkmcnt(1)
	v_fmac_f32_e32 v176, v192, v196
	v_fmac_f32_e32 v176, v193, v197
	v_fmac_f32_e32 v175, v195, v125
	ds_read_b128 v[122:125], v137 offset:30768
	ds_read_b128 v[200:203], v137 offset:31776
	v_fmac_f32_e32 v176, v194, v198
	v_fmac_f32_e32 v176, v195, v199
	ds_read_b128 v[196:199], v137 offset:32800
	ds_read_b128 v[204:207], v137 offset:31792
	v_fmac_f32_e32 v149, v191, v30
	s_waitcnt lgkmcnt(2)
	v_fmac_f32_e32 v177, v192, v200
	v_fmac_f32_e32 v150, v191, v34
	s_waitcnt lgkmcnt(1)
	v_fmac_f32_e32 v178, v192, v196
	v_fmac_f32_e32 v158, v191, v10
	v_fmac_f32_e32 v159, v191, v14
	v_fmac_f32_e32 v160, v191, v18
	v_fmac_f32_e32 v177, v193, v201
	v_fmac_f32_e32 v178, v193, v197
	v_fmac_f32_e32 v139, v191, v2
	v_fmac_f32_e32 v147, v191, v22
	v_fmac_f32_e32 v148, v191, v26
	v_fmac_f32_e32 v149, v190, v31
	v_fmac_f32_e32 v150, v190, v35
	v_fmac_f32_e32 v151, v191, v38
	v_fmac_f32_e32 v152, v191, v42
	v_fmac_f32_e32 v153, v191, v50
	v_fmac_f32_e32 v154, v191, v54
	v_fmac_f32_e32 v155, v191, v58
	v_fmac_f32_e32 v156, v191, v62
	v_fmac_f32_e32 v161, v191, v46
	v_fmac_f32_e32 v162, v191, v66
	v_fmac_f32_e32 v163, v191, v70
	v_fmac_f32_e32 v164, v191, v74
	v_fmac_f32_e32 v165, v191, v78
	v_fmac_f32_e32 v166, v191, v82
	v_fmac_f32_e32 v167, v191, v86
	v_fmac_f32_e32 v168, v191, v90
	v_fmac_f32_e32 v158, v190, v11
	v_fmac_f32_e32 v159, v190, v15
	v_fmac_f32_e32 v160, v190, v19
	v_fmac_f32_e32 v177, v194, v202
	v_fmac_f32_e32 v178, v194, v198
	v_fmac_f32_e32 v139, v190, v3
	v_fmac_f32_e32 v147, v190, v23
	v_fmac_f32_e32 v148, v190, v27
	v_fmac_f32_e32 v149, v189, v32
	v_fmac_f32_e32 v150, v189, v36
	v_fmac_f32_e32 v151, v190, v39
	v_fmac_f32_e32 v152, v190, v43
	v_fmac_f32_e32 v153, v190, v51
	v_fmac_f32_e32 v154, v190, v55
	v_fmac_f32_e32 v155, v190, v59
	v_fmac_f32_e32 v156, v190, v63
	v_fmac_f32_e32 v170, v191, v98
	v_fmac_f32_e32 v161, v190, v47
	v_fmac_f32_e32 v162, v190, v67
	v_fmac_f32_e32 v163, v190, v71
	v_fmac_f32_e32 v164, v190, v75
	v_fmac_f32_e32 v165, v190, v79
	v_fmac_f32_e32 v166, v190, v83
	v_fmac_f32_e32 v167, v190, v87
	v_fmac_f32_e32 v168, v190, v91
	v_fmac_f32_e32 v158, v189, v12
	v_fmac_f32_e32 v159, v189, v16
	v_fmac_f32_e32 v160, v189, v20
	v_fmac_f32_e32 v177, v195, v203
	ds_read_b128 v[200:203], v137 offset:32816
	ds_read_b128 v[208:211], v137 offset:33824
	v_fmac_f32_e32 v178, v195, v199
	ds_read_b128 v[196:199], v137 offset:33840
	v_fmac_f32_e32 v139, v189, v4
	v_fmac_f32_e32 v147, v189, v24
	v_fmac_f32_e32 v148, v189, v28
	v_fmac_f32_e32 v149, v188, v33
	v_fmac_f32_e32 v150, v188, v37
	v_fmac_f32_e32 v151, v189, v40
	v_fmac_f32_e32 v152, v189, v44
	v_fmac_f32_e32 v153, v189, v52
	v_fmac_f32_e32 v154, v189, v56
	v_fmac_f32_e32 v155, v189, v60
	v_fmac_f32_e32 v156, v189, v64
	v_fmac_f32_e32 v170, v190, v99
	v_fmac_f32_e32 v161, v189, v48
	v_fmac_f32_e32 v162, v189, v68
	v_fmac_f32_e32 v163, v189, v72
	v_fmac_f32_e32 v164, v189, v76
	v_fmac_f32_e32 v165, v189, v80
	v_fmac_f32_e32 v166, v189, v84
	v_fmac_f32_e32 v167, v189, v88
	v_fmac_f32_e32 v168, v189, v92
	v_fmac_f32_e32 v158, v188, v13
	v_fmac_f32_e32 v159, v188, v17
	v_fmac_f32_e32 v160, v188, v21
	ds_read_b128 v[10:13], v137 offset:64
	ds_read_b128 v[14:17], v137 offset:1088
	ds_read_b128 v[30:33], v137 offset:80
	ds_read_b128 v[18:21], v137 offset:2112
	ds_read_b128 v[34:37], v137 offset:1104
	v_fmac_f32_e32 v139, v188, v5
	v_fmac_f32_e32 v147, v188, v25
	v_fmac_f32_e32 v148, v188, v29
	v_fmac_f32_e32 v151, v188, v41
	v_fmac_f32_e32 v152, v188, v45
	v_fmac_f32_e32 v153, v188, v53
	v_fmac_f32_e32 v154, v188, v57
	v_fmac_f32_e32 v155, v188, v61
	v_fmac_f32_e32 v156, v188, v65
	v_fmac_f32_e32 v170, v189, v100
	v_fmac_f32_e32 v161, v188, v49
	v_fmac_f32_e32 v162, v188, v69
	v_fmac_f32_e32 v163, v188, v73
	v_fmac_f32_e32 v164, v188, v77
	v_fmac_f32_e32 v165, v188, v81
	v_fmac_f32_e32 v166, v188, v85
	v_fmac_f32_e32 v167, v188, v89
	v_fmac_f32_e32 v168, v188, v93
	ds_read_b128 v[22:25], v137 offset:3136
	ds_read_b128 v[38:41], v137 offset:2128
	ds_read_b128 v[26:29], v137 offset:4160
	ds_read_b128 v[42:45], v137 offset:3152
	ds_read_b128 v[62:65], v137 offset:5184
	ds_read_b128 v[46:49], v137 offset:4176
	ds_read_b128 v[70:73], v137 offset:6208
	ds_read_b128 v[50:53], v137 offset:5200
	ds_read_b128 v[74:77], v137 offset:7232
	ds_read_b128 v[54:57], v137 offset:6224
	ds_read_b128 v[78:81], v137 offset:8256
	ds_read_b128 v[58:61], v137 offset:7248
	ds_read_b128 v[82:85], v137 offset:9280
	ds_read_b128 v[66:69], v137 offset:8272
	ds_read_b128 v[86:89], v137 offset:10304
	ds_read_b128 v[90:93], v137 offset:11328
	ds_read_b128 v[2:5], v137 offset:9296
	v_fmac_f32_e32 v170, v188, v101
	ds_read_b128 v[98:101], v137 offset:13376
	v_fmac_f32_e32 v169, v191, v94
	v_fmac_f32_e32 v171, v191, v102
	s_waitcnt lgkmcnt(14)
	v_fmac_f32_e32 v148, v184, v18
	s_waitcnt lgkmcnt(3)
	v_fmac_f32_e32 v156, v184, v86
	v_fmac_f32_e32 v157, v191, v6
	v_fmac_f32_e32 v169, v190, v95
	v_fmac_f32_e32 v171, v190, v103
	v_fmac_f32_e32 v148, v185, v19
	v_fmac_f32_e32 v156, v185, v87
	v_fmac_f32_e32 v157, v190, v7
	v_fmac_f32_e32 v169, v189, v96
	v_fmac_f32_e32 v171, v189, v104
	v_fmac_f32_e32 v154, v184, v78
	v_fmac_f32_e32 v148, v186, v20
	v_fmac_f32_e32 v156, v186, v88
	v_fmac_f32_e32 v157, v189, v8
	v_fmac_f32_e32 v169, v188, v97
	v_fmac_f32_e32 v171, v188, v105
	ds_read_b128 v[94:97], v137 offset:12352
	v_fmac_f32_e32 v148, v187, v21
	ds_read_b128 v[18:21], v137 offset:13392
	s_waitcnt lgkmcnt(2)
	v_fmac_f32_e32 v159, v184, v98
	ds_read_b128 v[102:105], v137 offset:14400
	v_fmac_f32_e32 v154, v185, v79
	v_fmac_f32_e32 v156, v187, v89
	ds_read_b128 v[86:89], v137 offset:18496
	v_fmac_f32_e32 v157, v188, v9
	v_fmac_f32_e32 v154, v186, v80
	v_fmac_f32_e32 v159, v185, v99
	v_fmac_f32_e32 v147, v184, v14
	v_fmac_f32_e32 v149, v184, v22
	v_fmac_f32_e32 v153, v184, v74
	v_fmac_f32_e32 v155, v184, v82
	v_fmac_f32_e32 v157, v184, v90
	v_fmac_f32_e32 v154, v187, v81
	ds_read_b128 v[78:81], v137 offset:16448
	v_fmac_f32_e32 v159, v186, v100
	v_fmac_f32_e32 v147, v185, v15
	v_fmac_f32_e32 v149, v185, v23
	v_fmac_f32_e32 v153, v185, v75
	v_fmac_f32_e32 v155, v185, v83
	v_fmac_f32_e32 v157, v185, v91
	v_fmac_f32_e32 v159, v187, v101
	ds_read_b128 v[98:101], v137 offset:21568
	v_fmac_f32_e32 v151, v184, v62
	v_fmac_f32_e32 v147, v186, v16
	v_fmac_f32_e32 v149, v186, v24
	v_fmac_f32_e32 v153, v186, v76
	v_fmac_f32_e32 v155, v186, v84
	v_fmac_f32_e32 v157, v186, v92
	v_fmac_f32_e32 v147, v187, v17
	ds_read_b128 v[14:17], v137 offset:12368
	s_waitcnt lgkmcnt(6)
	v_fmac_f32_e32 v158, v184, v94
	v_fmac_f32_e32 v149, v187, v25
	v_fmac_f32_e32 v151, v185, v63
	ds_read_b128 v[22:25], v137 offset:14416
	s_waitcnt lgkmcnt(5)
	v_fmac_f32_e32 v160, v184, v102
	v_fmac_f32_e32 v153, v187, v77
	v_fmac_f32_e32 v155, v187, v85
	v_fmac_f32_e32 v157, v187, v93
	ds_read_b128 v[82:85], v137 offset:17472
	ds_read_b128 v[74:77], v137 offset:18512
	s_waitcnt lgkmcnt(6)
	v_fmac_f32_e32 v164, v184, v86
	ds_read_b128 v[90:93], v137 offset:19520
	v_fmac_f32_e32 v151, v186, v64
	v_fmac_f32_e32 v158, v185, v95
	v_fmac_f32_e32 v160, v185, v103
	v_fmac_f32_e32 v164, v185, v87
	v_fmac_f32_e32 v152, v184, v70
	v_fmac_f32_e32 v151, v187, v65
	ds_read_b128 v[62:65], v137 offset:16464
	s_waitcnt lgkmcnt(7)
	v_fmac_f32_e32 v162, v184, v78
	v_fmac_f32_e32 v158, v186, v96
	v_fmac_f32_e32 v160, v186, v104
	v_fmac_f32_e32 v164, v186, v88
	v_fmac_f32_e32 v172, v191, v106
	v_fmac_f32_e32 v152, v185, v71
	v_fmac_f32_e32 v158, v187, v97
	v_fmac_f32_e32 v160, v187, v105
	v_fmac_f32_e32 v162, v185, v79
	ds_read_b128 v[94:97], v137 offset:20544
	v_fmac_f32_e32 v164, v187, v89
	ds_read_b128 v[102:105], v137 offset:22592
	ds_read_b128 v[86:89], v137 offset:21584
	s_waitcnt lgkmcnt(9)
	v_fmac_f32_e32 v167, v184, v98
	v_fmac_f32_e32 v172, v190, v107
	v_fmac_f32_e32 v152, v186, v72
	v_fmac_f32_e32 v162, v186, v80
	v_fmac_f32_e32 v167, v185, v99
	v_fmac_f32_e32 v172, v189, v108
	v_fmac_f32_e32 v152, v187, v73
	ds_read_b128 v[70:73], v137 offset:17488
	s_waitcnt lgkmcnt(7)
	v_fmac_f32_e32 v163, v184, v82
	v_fmac_f32_e32 v162, v187, v81
	ds_read_b128 v[78:81], v137 offset:19536
	s_waitcnt lgkmcnt(6)
	v_fmac_f32_e32 v165, v184, v90
	v_fmac_f32_e32 v167, v186, v100
	v_fmac_f32_e32 v172, v188, v109
	ds_read_b128 v[106:109], v137 offset:15424
	v_fmac_f32_e32 v163, v185, v83
	v_fmac_f32_e32 v165, v185, v91
	v_fmac_f32_e32 v167, v187, v101
	ds_read_b128 v[98:101], v137 offset:23616
	v_fmac_f32_e32 v163, v186, v84
	v_fmac_f32_e32 v165, v186, v92
	v_fmac_f32_e32 v139, v184, v10
	v_fmac_f32_e32 v150, v184, v26
	v_fmac_f32_e32 v163, v187, v85
	ds_read_b128 v[82:85], v137 offset:20560
	s_waitcnt lgkmcnt(7)
	v_fmac_f32_e32 v166, v184, v94
	v_fmac_f32_e32 v165, v187, v93
	ds_read_b128 v[90:93], v137 offset:22608
	s_waitcnt lgkmcnt(7)
	v_fmac_f32_e32 v168, v184, v102
	v_fmac_f32_e32 v139, v185, v11
	v_fmac_f32_e32 v150, v185, v27
	v_fmac_f32_e32 v166, v185, v95
	v_fmac_f32_e32 v168, v185, v103
	v_fmac_f32_e32 v139, v186, v12
	v_fmac_f32_e32 v150, v186, v28
	v_fmac_f32_e32 v166, v186, v96
	v_fmac_f32_e32 v168, v186, v104
	ds_read_b128 v[6:9], v137 offset:10320
	v_fmac_f32_e32 v139, v187, v13
	ds_read_b128 v[10:13], v137 offset:11344
	v_fmac_f32_e32 v150, v187, v29
	ds_read_b128 v[26:29], v137 offset:15440
	s_waitcnt lgkmcnt(6)
	v_fmac_f32_e32 v161, v184, v106
	v_fmac_f32_e32 v166, v187, v97
	v_fmac_f32_e32 v168, v187, v105
	ds_read_b128 v[102:105], v137 offset:24640
	ds_read_b128 v[94:97], v137 offset:23632
	s_waitcnt lgkmcnt(7)
	v_fmac_f32_e32 v169, v184, v98
	v_fmac_f32_e32 v161, v185, v107
	v_fmac_f32_e32 v169, v185, v99
	v_fmac_f32_e32 v161, v186, v108
	v_fmac_f32_e32 v169, v186, v100
	v_fmac_f32_e32 v161, v187, v109
	v_fmac_f32_e32 v169, v187, v101
	ds_read_b128 v[98:101], v137 offset:24656
	ds_read_b128 v[106:109], v137 offset:25664
	v_fmac_f32_e32 v173, v191, v110
	s_waitcnt lgkmcnt(3)
	v_fmac_f32_e32 v170, v184, v102
	v_fmac_f32_e32 v173, v190, v111
	v_fmac_f32_e32 v170, v185, v103
	v_fmac_f32_e32 v173, v189, v112
	v_fmac_f32_e32 v170, v186, v104
	v_fmac_f32_e32 v173, v188, v113
	v_fmac_f32_e32 v170, v187, v105
	ds_read_b128 v[110:113], v137 offset:26688
	ds_read_b128 v[102:105], v137 offset:25680
	v_fmac_f32_e32 v174, v191, v114
	s_waitcnt lgkmcnt(2)
	v_fmac_f32_e32 v171, v184, v106
	v_fmac_f32_e32 v174, v190, v115
	v_fmac_f32_e32 v171, v185, v107
	v_fmac_f32_e32 v174, v189, v116
	v_fmac_f32_e32 v171, v186, v108
	v_fmac_f32_e32 v175, v191, v118
	v_fmac_f32_e32 v174, v188, v117
	v_fmac_f32_e32 v171, v187, v109
	ds_read_b128 v[106:109], v137 offset:26704
	ds_read_b128 v[114:117], v137 offset:27712
	s_waitcnt lgkmcnt(3)
	v_fmac_f32_e32 v172, v184, v110
	v_fmac_f32_e32 v175, v190, v119
	v_fmac_f32_e32 v172, v185, v111
	v_fmac_f32_e32 v175, v189, v120
	v_fmac_f32_e32 v172, v186, v112
	v_fmac_f32_e32 v179, v192, v208
	v_fmac_f32_e32 v175, v188, v121
	v_fmac_f32_e32 v172, v187, v113
	ds_read_b128 v[118:121], v137 offset:28736
	ds_read_b128 v[110:113], v137 offset:27728
	v_fmac_f32_e32 v179, v193, v209
	v_fmac_f32_e32 v179, v194, v210
	v_fmac_f32_e32 v176, v191, v122
	s_waitcnt lgkmcnt(2)
	v_fmac_f32_e32 v173, v184, v114
	v_fmac_f32_e32 v179, v195, v211
	v_fmac_f32_e32 v176, v190, v123
	v_fmac_f32_e32 v173, v185, v115
	v_fmac_f32_e32 v177, v191, v204
	v_fmac_f32_e32 v178, v191, v200
	v_fmac_f32_e32 v179, v191, v196
	v_fmac_f32_e32 v176, v189, v124
	v_fmac_f32_e32 v173, v186, v116
	s_waitcnt lgkmcnt(1)
	v_fmac_f32_e32 v174, v184, v118
	v_fmac_f32_e32 v177, v190, v205
	v_fmac_f32_e32 v178, v190, v201
	v_fmac_f32_e32 v179, v190, v197
	v_fmac_f32_e32 v176, v188, v125
	v_fmac_f32_e32 v173, v187, v117
	ds_read_b128 v[114:117], v137 offset:28752
	ds_read_b128 v[122:125], v137 offset:29760
	v_fmac_f32_e32 v174, v185, v119
	v_fmac_f32_e32 v177, v189, v206
	v_fmac_f32_e32 v178, v189, v202
	v_fmac_f32_e32 v179, v189, v198
	v_fmac_f32_e32 v174, v186, v120
	v_fmac_f32_e32 v177, v188, v207
	v_fmac_f32_e32 v178, v188, v203
	v_fmac_f32_e32 v179, v188, v199
	v_fmac_f32_e32 v174, v187, v121
	ds_read_b128 v[188:191], v137 offset:30784
	ds_read_b128 v[118:121], v137 offset:29776
	s_waitcnt lgkmcnt(2)
	v_fmac_f32_e32 v175, v184, v122
	v_fmac_f32_e32 v175, v185, v123
	v_fmac_f32_e32 v175, v186, v124
	s_waitcnt lgkmcnt(1)
	v_fmac_f32_e32 v176, v184, v188
	v_fmac_f32_e32 v176, v185, v189
	v_fmac_f32_e32 v175, v187, v125
	ds_read_b128 v[122:125], v137 offset:30800
	ds_read_b128 v[192:195], v137 offset:31808
	v_fmac_f32_e32 v176, v186, v190
	v_fmac_f32_e32 v176, v187, v191
	ds_read_b128 v[188:191], v137 offset:32832
	ds_read_b128 v[196:199], v137 offset:31824
	v_fmac_f32_e32 v139, v183, v30
	s_waitcnt lgkmcnt(2)
	v_fmac_f32_e32 v177, v184, v192
	v_fmac_f32_e32 v147, v183, v34
	s_waitcnt lgkmcnt(1)
	v_fmac_f32_e32 v178, v184, v188
	v_fmac_f32_e32 v148, v183, v38
	v_fmac_f32_e32 v149, v183, v42
	v_fmac_f32_e32 v150, v183, v46
	v_fmac_f32_e32 v151, v183, v50
	v_fmac_f32_e32 v152, v183, v54
	v_fmac_f32_e32 v153, v183, v58
	v_fmac_f32_e32 v154, v183, v66
	v_fmac_f32_e32 v155, v183, v2
	v_fmac_f32_e32 v156, v183, v6
	v_fmac_f32_e32 v157, v183, v10
	v_fmac_f32_e32 v160, v183, v22
	v_fmac_f32_e32 v161, v183, v26
	v_fmac_f32_e32 v162, v183, v62
	v_fmac_f32_e32 v163, v183, v70
	v_fmac_f32_e32 v164, v183, v74
	v_fmac_f32_e32 v165, v183, v78
	v_fmac_f32_e32 v166, v183, v82
	v_fmac_f32_e32 v167, v183, v86
	v_fmac_f32_e32 v168, v183, v90
	v_fmac_f32_e32 v177, v185, v193
	v_fmac_f32_e32 v178, v185, v189
	v_fmac_f32_e32 v139, v182, v31
	v_fmac_f32_e32 v147, v182, v35
	v_fmac_f32_e32 v148, v182, v39
	v_fmac_f32_e32 v149, v182, v43
	v_fmac_f32_e32 v150, v182, v47
	v_fmac_f32_e32 v151, v182, v51
	v_fmac_f32_e32 v152, v182, v55
	v_fmac_f32_e32 v153, v182, v59
	v_fmac_f32_e32 v154, v182, v67
	v_fmac_f32_e32 v155, v182, v3
	v_fmac_f32_e32 v156, v182, v7
	v_fmac_f32_e32 v157, v182, v11
	v_fmac_f32_e32 v160, v182, v23
	v_fmac_f32_e32 v161, v182, v27
	v_fmac_f32_e32 v162, v182, v63
	v_fmac_f32_e32 v163, v182, v71
	v_fmac_f32_e32 v164, v182, v75
	v_fmac_f32_e32 v165, v182, v79
	v_fmac_f32_e32 v166, v182, v83
	v_fmac_f32_e32 v167, v182, v87
	v_fmac_f32_e32 v168, v182, v91
	v_fmac_f32_e32 v177, v186, v194
	v_fmac_f32_e32 v178, v186, v190
	v_fmac_f32_e32 v139, v181, v32
	v_fmac_f32_e32 v147, v181, v36
	v_fmac_f32_e32 v148, v181, v40
	v_fmac_f32_e32 v149, v181, v44
	v_fmac_f32_e32 v150, v181, v48
	v_fmac_f32_e32 v151, v181, v52
	v_fmac_f32_e32 v152, v181, v56
	v_fmac_f32_e32 v153, v181, v60
	v_fmac_f32_e32 v154, v181, v68
	v_fmac_f32_e32 v158, v183, v14
	v_fmac_f32_e32 v169, v183, v94
	v_fmac_f32_e32 v170, v183, v98
	v_fmac_f32_e32 v171, v183, v102
	v_fmac_f32_e32 v172, v183, v106
	v_fmac_f32_e32 v155, v181, v4
	v_fmac_f32_e32 v156, v181, v8
	v_fmac_f32_e32 v157, v181, v12
	v_fmac_f32_e32 v160, v181, v24
	v_fmac_f32_e32 v161, v181, v28
	v_fmac_f32_e32 v162, v181, v64
	v_fmac_f32_e32 v163, v181, v72
	v_fmac_f32_e32 v164, v181, v76
	v_fmac_f32_e32 v165, v181, v80
	v_fmac_f32_e32 v166, v181, v84
	v_fmac_f32_e32 v167, v181, v88
	v_fmac_f32_e32 v168, v181, v92
	v_fmac_f32_e32 v177, v187, v195
	ds_read_b128 v[192:195], v137 offset:32848
	ds_read_b128 v[200:203], v137 offset:33856
	v_fmac_f32_e32 v178, v187, v191
	ds_read_b128 v[188:191], v137 offset:33872
	v_fmac_f32_e32 v139, v180, v33
	v_fmac_f32_e32 v147, v180, v37
	v_fmac_f32_e32 v148, v180, v41
	v_fmac_f32_e32 v149, v180, v45
	v_fmac_f32_e32 v150, v180, v49
	v_fmac_f32_e32 v151, v180, v53
	v_fmac_f32_e32 v152, v180, v57
	v_fmac_f32_e32 v153, v180, v61
	v_fmac_f32_e32 v154, v180, v69
	v_fmac_f32_e32 v158, v182, v15
	v_fmac_f32_e32 v169, v182, v95
	v_fmac_f32_e32 v170, v182, v99
	v_fmac_f32_e32 v171, v182, v103
	v_fmac_f32_e32 v172, v182, v107
	v_fmac_f32_e32 v155, v180, v5
	v_fmac_f32_e32 v156, v180, v9
	v_fmac_f32_e32 v157, v180, v13
	v_fmac_f32_e32 v160, v180, v25
	v_fmac_f32_e32 v161, v180, v29
	v_fmac_f32_e32 v162, v180, v65
	v_fmac_f32_e32 v163, v180, v73
	v_fmac_f32_e32 v164, v180, v77
	v_fmac_f32_e32 v165, v180, v81
	v_fmac_f32_e32 v166, v180, v85
	v_fmac_f32_e32 v167, v180, v89
	v_fmac_f32_e32 v168, v180, v93
	ds_read_b128 v[22:25], v137 offset:96
	ds_read_b128 v[26:29], v137 offset:1120
	ds_read_b128 v[42:45], v137 offset:112
	ds_read_b128 v[30:33], v137 offset:2144
	ds_read_b128 v[46:49], v137 offset:1136
	ds_read_b128 v[34:37], v137 offset:3168
	ds_read_b128 v[50:53], v137 offset:2160
	ds_read_b128 v[38:41], v137 offset:4192
	ds_read_b128 v[54:57], v137 offset:3184
	ds_read_b128 v[70:73], v137 offset:5216
	ds_read_b128 v[58:61], v137 offset:4208
	ds_read_b128 v[74:77], v137 offset:6240
	ds_read_b128 v[62:65], v137 offset:5232
	ds_read_b128 v[78:81], v137 offset:7264
	ds_read_b128 v[66:69], v137 offset:6256
	ds_read_b128 v[82:85], v137 offset:8288
	ds_read_b128 v[2:5], v137 offset:7280
	ds_read_b128 v[86:89], v137 offset:9312
	ds_read_b128 v[6:9], v137 offset:8304
	ds_read_b128 v[90:93], v137 offset:10336
	ds_read_b128 v[10:13], v137 offset:9328
	v_fmac_f32_e32 v158, v181, v16
	v_fmac_f32_e32 v169, v181, v96
	v_fmac_f32_e32 v170, v181, v100
	v_fmac_f32_e32 v171, v181, v104
	v_fmac_f32_e32 v172, v181, v108
	v_fmac_f32_e32 v158, v180, v17
	v_fmac_f32_e32 v169, v180, v97
	v_fmac_f32_e32 v170, v180, v101
	v_fmac_f32_e32 v171, v180, v105
	v_fmac_f32_e32 v172, v180, v109
	ds_read_b128 v[94:97], v137 offset:11360
	ds_read_b128 v[98:101], v137 offset:12384
	ds_read_b128 v[14:17], v137 offset:10352
	ds_read_b128 v[102:105], v137 offset:13408
	ds_read_b128 v[106:109], v137 offset:14432
	v_fmac_f32_e32 v159, v183, v18
	v_fmac_f32_e32 v159, v182, v19
	s_waitcnt lgkmcnt(14)
	v_fmac_f32_e32 v147, v143, v26
	v_fmac_f32_e32 v148, v143, v30
	s_waitcnt lgkmcnt(8)
	v_fmac_f32_e32 v155, v143, v86
	s_waitcnt lgkmcnt(6)
	v_fmac_f32_e32 v156, v143, v90
	v_fmac_f32_e32 v159, v181, v20
	v_fmac_f32_e32 v147, v144, v27
	v_fmac_f32_e32 v148, v144, v31
	v_fmac_f32_e32 v155, v144, v87
	v_fmac_f32_e32 v156, v144, v91
	v_fmac_f32_e32 v159, v180, v21
	v_fmac_f32_e32 v147, v145, v28
	v_fmac_f32_e32 v148, v145, v32
	v_fmac_f32_e32 v155, v145, v88
	v_fmac_f32_e32 v156, v145, v92
	v_fmac_f32_e32 v173, v183, v110
	v_fmac_f32_e32 v147, v146, v29
	v_fmac_f32_e32 v148, v146, v33
	ds_read_b128 v[26:29], v137 offset:13424
	s_waitcnt lgkmcnt(2)
	v_fmac_f32_e32 v159, v143, v102
	ds_read_b128 v[30:33], v137 offset:14448
	s_waitcnt lgkmcnt(2)
	v_fmac_f32_e32 v160, v143, v106
	v_fmac_f32_e32 v155, v146, v89
	ds_read_b128 v[86:89], v137 offset:17504
	v_fmac_f32_e32 v156, v146, v93
	ds_read_b128 v[90:93], v137 offset:18528
	v_fmac_f32_e32 v173, v182, v111
	v_fmac_f32_e32 v159, v144, v103
	v_fmac_f32_e32 v160, v144, v107
	v_fmac_f32_e32 v173, v181, v112
	v_fmac_f32_e32 v151, v143, v70
	v_fmac_f32_e32 v152, v143, v74
	v_fmac_f32_e32 v159, v145, v104
	v_fmac_f32_e32 v160, v145, v108
	v_fmac_f32_e32 v173, v180, v113
	v_fmac_f32_e32 v151, v144, v71
	ds_read_b128 v[110:113], v137 offset:15456
	v_fmac_f32_e32 v152, v144, v75
	v_fmac_f32_e32 v159, v146, v105
	v_fmac_f32_e32 v160, v146, v109
	ds_read_b128 v[102:105], v137 offset:21600
	ds_read_b128 v[106:109], v137 offset:22624
	v_fmac_f32_e32 v151, v145, v72
	v_fmac_f32_e32 v152, v145, v76
	v_fmac_f32_e32 v149, v143, v34
	v_fmac_f32_e32 v157, v143, v94
	v_fmac_f32_e32 v158, v143, v98
	v_fmac_f32_e32 v151, v146, v73
	v_fmac_f32_e32 v152, v146, v77
	ds_read_b128 v[70:73], v137 offset:17520
	s_waitcnt lgkmcnt(5)
	v_fmac_f32_e32 v163, v143, v86
	ds_read_b128 v[74:77], v137 offset:18544
	s_waitcnt lgkmcnt(5)
	v_fmac_f32_e32 v164, v143, v90
	v_fmac_f32_e32 v149, v144, v35
	v_fmac_f32_e32 v157, v144, v95
	v_fmac_f32_e32 v158, v144, v99
	v_fmac_f32_e32 v163, v144, v87
	v_fmac_f32_e32 v164, v144, v91
	v_fmac_f32_e32 v149, v145, v36
	v_fmac_f32_e32 v157, v145, v96
	v_fmac_f32_e32 v158, v145, v100
	v_fmac_f32_e32 v163, v145, v88
	v_fmac_f32_e32 v164, v145, v92
	v_fmac_f32_e32 v174, v183, v114
	v_fmac_f32_e32 v149, v146, v37
	ds_read_b128 v[34:37], v137 offset:15472
	s_waitcnt lgkmcnt(5)
	v_fmac_f32_e32 v161, v143, v110
	v_fmac_f32_e32 v157, v146, v97
	v_fmac_f32_e32 v158, v146, v101
	ds_read_b128 v[94:97], v137 offset:19552
	ds_read_b128 v[98:101], v137 offset:20576
	v_fmac_f32_e32 v163, v146, v89
	v_fmac_f32_e32 v164, v146, v93
	ds_read_b128 v[86:89], v137 offset:21616
	s_waitcnt lgkmcnt(7)
	v_fmac_f32_e32 v167, v143, v102
	ds_read_b128 v[90:93], v137 offset:22640
	s_waitcnt lgkmcnt(7)
	v_fmac_f32_e32 v168, v143, v106
	v_fmac_f32_e32 v174, v182, v115
	v_fmac_f32_e32 v161, v144, v111
	v_fmac_f32_e32 v167, v144, v103
	v_fmac_f32_e32 v168, v144, v107
	v_fmac_f32_e32 v174, v181, v116
	v_fmac_f32_e32 v153, v143, v78
	v_fmac_f32_e32 v154, v143, v82
	v_fmac_f32_e32 v161, v145, v112
	v_fmac_f32_e32 v167, v145, v104
	v_fmac_f32_e32 v168, v145, v108
	v_fmac_f32_e32 v174, v180, v117
	v_fmac_f32_e32 v153, v144, v79
	ds_read_b128 v[114:117], v137 offset:16480
	v_fmac_f32_e32 v154, v144, v83
	v_fmac_f32_e32 v161, v146, v113
	ds_read_b128 v[110:113], v137 offset:23648
	v_fmac_f32_e32 v167, v146, v105
	ds_read_b128 v[102:105], v137 offset:24672
	v_fmac_f32_e32 v168, v146, v109
	ds_read_b128 v[106:109], v137 offset:25696
	v_fmac_f32_e32 v153, v145, v80
	v_fmac_f32_e32 v154, v145, v84
	v_fmac_f32_e32 v150, v143, v38
	v_fmac_f32_e32 v153, v146, v81
	v_fmac_f32_e32 v154, v146, v85
	ds_read_b128 v[78:81], v137 offset:19568
	s_waitcnt lgkmcnt(8)
	v_fmac_f32_e32 v165, v143, v94
	ds_read_b128 v[82:85], v137 offset:20592
	s_waitcnt lgkmcnt(8)
	v_fmac_f32_e32 v166, v143, v98
	v_fmac_f32_e32 v150, v144, v39
	v_fmac_f32_e32 v165, v144, v95
	v_fmac_f32_e32 v166, v144, v99
	v_fmac_f32_e32 v150, v145, v40
	v_fmac_f32_e32 v165, v145, v96
	v_fmac_f32_e32 v166, v145, v100
	v_fmac_f32_e32 v139, v143, v22
	v_fmac_f32_e32 v150, v146, v41
	ds_read_b128 v[38:41], v137 offset:16496
	s_waitcnt lgkmcnt(6)
	v_fmac_f32_e32 v162, v143, v114
	v_fmac_f32_e32 v165, v146, v97
	v_fmac_f32_e32 v166, v146, v101
	ds_read_b128 v[94:97], v137 offset:23664
	s_waitcnt lgkmcnt(6)
	v_fmac_f32_e32 v169, v143, v110
	ds_read_b128 v[98:101], v137 offset:24688
	s_waitcnt lgkmcnt(6)
	v_fmac_f32_e32 v170, v143, v102
	s_waitcnt lgkmcnt(5)
	v_fmac_f32_e32 v171, v143, v106
	v_fmac_f32_e32 v139, v144, v23
	v_fmac_f32_e32 v162, v144, v115
	v_fmac_f32_e32 v169, v144, v111
	v_fmac_f32_e32 v170, v144, v103
	v_fmac_f32_e32 v171, v144, v107
	v_fmac_f32_e32 v139, v145, v24
	v_fmac_f32_e32 v162, v145, v116
	v_fmac_f32_e32 v169, v145, v112
	v_fmac_f32_e32 v170, v145, v104
	v_fmac_f32_e32 v171, v145, v108
	ds_read_b128 v[18:21], v137 offset:11376
	v_fmac_f32_e32 v139, v146, v25
	ds_read_b128 v[22:25], v137 offset:12400
	v_fmac_f32_e32 v162, v146, v117
	v_fmac_f32_e32 v169, v146, v113
	v_fmac_f32_e32 v170, v146, v105
	ds_read_b128 v[110:113], v137 offset:26720
	ds_read_b128 v[102:105], v137 offset:25712
	v_fmac_f32_e32 v171, v146, v109
	ds_read_b128 v[106:109], v137 offset:26736
	ds_read_b128 v[114:117], v137 offset:27744
	v_fmac_f32_e32 v175, v183, v118
	s_waitcnt lgkmcnt(3)
	v_fmac_f32_e32 v172, v143, v110
	v_fmac_f32_e32 v176, v183, v122
	v_fmac_f32_e32 v175, v182, v119
	v_fmac_f32_e32 v172, v144, v111
	s_waitcnt lgkmcnt(0)
	v_fmac_f32_e32 v173, v143, v114
	v_fmac_f32_e32 v176, v182, v123
	v_fmac_f32_e32 v175, v181, v120
	v_fmac_f32_e32 v172, v145, v112
	v_fmac_f32_e32 v173, v144, v115
	v_fmac_f32_e32 v179, v184, v200
	v_fmac_f32_e32 v176, v181, v124
	v_fmac_f32_e32 v175, v180, v121
	v_fmac_f32_e32 v172, v146, v113
	ds_read_b128 v[118:121], v137 offset:28768
	ds_read_b128 v[110:113], v137 offset:27760
	v_fmac_f32_e32 v173, v145, v116
	v_fmac_f32_e32 v179, v185, v201
	v_fmac_f32_e32 v176, v180, v125
	v_fmac_f32_e32 v173, v146, v117
	ds_read_b128 v[114:117], v137 offset:28784
	ds_read_b128 v[122:125], v137 offset:29792
	v_fmac_f32_e32 v179, v186, v202
	v_fmac_f32_e32 v179, v187, v203
	v_fmac_f32_e32 v177, v183, v196
	v_fmac_f32_e32 v178, v183, v192
	v_fmac_f32_e32 v179, v183, v188
	s_waitcnt lgkmcnt(3)
	v_fmac_f32_e32 v174, v143, v118
	v_fmac_f32_e32 v177, v182, v197
	v_fmac_f32_e32 v178, v182, v193
	v_fmac_f32_e32 v179, v182, v189
	v_fmac_f32_e32 v174, v144, v119
	v_fmac_f32_e32 v177, v181, v198
	v_fmac_f32_e32 v178, v181, v194
	v_fmac_f32_e32 v179, v181, v190
	v_fmac_f32_e32 v174, v145, v120
	s_waitcnt lgkmcnt(0)
	v_fmac_f32_e32 v175, v143, v122
	v_fmac_f32_e32 v177, v180, v199
	v_fmac_f32_e32 v178, v180, v195
	v_fmac_f32_e32 v179, v180, v191
	v_fmac_f32_e32 v174, v146, v121
	ds_read_b128 v[180:183], v137 offset:30816
	ds_read_b128 v[118:121], v137 offset:29808
	v_fmac_f32_e32 v175, v144, v123
	v_fmac_f32_e32 v175, v145, v124
	v_fmac_f32_e32 v175, v146, v125
	ds_read_b128 v[122:125], v137 offset:30832
	ds_read_b128 v[184:187], v137 offset:31840
	s_waitcnt lgkmcnt(3)
	v_fmac_f32_e32 v176, v143, v180
	v_fmac_f32_e32 v176, v144, v181
	v_fmac_f32_e32 v176, v145, v182
	v_fmac_f32_e32 v176, v146, v183
	ds_read_b128 v[180:183], v137 offset:32864
	ds_read_b128 v[188:191], v137 offset:31856
	s_waitcnt lgkmcnt(2)
	v_fmac_f32_e32 v177, v143, v184
	v_fmac_f32_e32 v177, v144, v185
	v_fmac_f32_e32 v177, v145, v186
	v_fmac_f32_e32 v177, v146, v187
	ds_read_b128 v[184:187], v137 offset:32880
	ds_read_b128 v[192:195], v137 offset:33888
	s_waitcnt lgkmcnt(3)
	v_fmac_f32_e32 v178, v143, v180
	v_fmac_f32_e32 v178, v144, v181
	v_fmac_f32_e32 v178, v145, v182
	v_fmac_f32_e32 v178, v146, v183
	ds_read_b128 v[180:183], v137 offset:33904
	s_waitcnt lgkmcnt(1)
	v_fmac_f32_e32 v179, v143, v192
	v_fmac_f32_e32 v179, v144, v193
	v_fmac_f32_e32 v179, v145, v194
	v_fmac_f32_e32 v179, v146, v195
	v_fmac_f32_e32 v139, v142, v42
	v_fmac_f32_e32 v147, v142, v46
	v_fmac_f32_e32 v139, v141, v43
	v_fmac_f32_e32 v147, v141, v47
	v_fmac_f32_e32 v148, v142, v50
	v_fmac_f32_e32 v149, v142, v54
	v_fmac_f32_e32 v150, v142, v58
	v_fmac_f32_e32 v151, v142, v62
	v_fmac_f32_e32 v152, v142, v66
	v_fmac_f32_e32 v153, v142, v2
	v_fmac_f32_e32 v154, v142, v6
	v_fmac_f32_e32 v155, v142, v10
	v_fmac_f32_e32 v156, v142, v14
	v_fmac_f32_e32 v157, v142, v18
	v_fmac_f32_e32 v158, v142, v22
	v_fmac_f32_e32 v159, v142, v26
	v_fmac_f32_e32 v160, v142, v30
	v_fmac_f32_e32 v161, v142, v34
	v_fmac_f32_e32 v162, v142, v38
	v_fmac_f32_e32 v163, v142, v70
	v_fmac_f32_e32 v164, v142, v74
	v_fmac_f32_e32 v165, v142, v78
	v_fmac_f32_e32 v166, v142, v82
	v_fmac_f32_e32 v167, v142, v86
	v_fmac_f32_e32 v168, v142, v90
	v_fmac_f32_e32 v169, v142, v94
	v_fmac_f32_e32 v170, v142, v98
	v_fmac_f32_e32 v171, v142, v102
	v_fmac_f32_e32 v172, v142, v106
	v_fmac_f32_e32 v173, v142, v110
	v_fmac_f32_e32 v174, v142, v114
	v_fmac_f32_e32 v175, v142, v118
	v_fmac_f32_e32 v176, v142, v122
	v_fmac_f32_e32 v177, v142, v188
	v_fmac_f32_e32 v178, v142, v184
	s_waitcnt lgkmcnt(0)
	v_fmac_f32_e32 v179, v142, v180
	v_fmac_f32_e32 v139, v140, v44
	v_fmac_f32_e32 v147, v140, v48
	v_fmac_f32_e32 v148, v141, v51
	v_fmac_f32_e32 v149, v141, v55
	v_fmac_f32_e32 v150, v141, v59
	v_fmac_f32_e32 v151, v141, v63
	v_fmac_f32_e32 v152, v141, v67
	v_fmac_f32_e32 v153, v141, v3
	v_fmac_f32_e32 v154, v141, v7
	v_fmac_f32_e32 v155, v141, v11
	v_fmac_f32_e32 v156, v141, v15
	v_fmac_f32_e32 v157, v141, v19
	v_fmac_f32_e32 v158, v141, v23
	v_fmac_f32_e32 v159, v141, v27
	v_fmac_f32_e32 v160, v141, v31
	v_fmac_f32_e32 v161, v141, v35
	v_fmac_f32_e32 v162, v141, v39
	v_fmac_f32_e32 v163, v141, v71
	v_fmac_f32_e32 v164, v141, v75
	v_fmac_f32_e32 v165, v141, v79
	v_fmac_f32_e32 v166, v141, v83
	v_fmac_f32_e32 v167, v141, v87
	v_fmac_f32_e32 v168, v141, v91
	v_fmac_f32_e32 v169, v141, v95
	v_fmac_f32_e32 v170, v141, v99
	v_fmac_f32_e32 v171, v141, v103
	v_fmac_f32_e32 v172, v141, v107
	v_fmac_f32_e32 v173, v141, v111
	v_fmac_f32_e32 v174, v141, v115
	v_fmac_f32_e32 v175, v141, v119
	v_fmac_f32_e32 v176, v141, v123
	v_fmac_f32_e32 v177, v141, v189
	v_fmac_f32_e32 v178, v141, v185
	v_fmac_f32_e32 v179, v141, v181
	v_fmac_f32_e32 v139, v128, v45
	v_fmac_f32_e32 v147, v128, v49
	v_fmac_f32_e32 v148, v140, v52
	v_fmac_f32_e32 v149, v140, v56
	v_fmac_f32_e32 v150, v140, v60
	v_fmac_f32_e32 v151, v140, v64
	v_fmac_f32_e32 v152, v140, v68
	v_fmac_f32_e32 v153, v140, v4
	v_fmac_f32_e32 v154, v140, v8
	v_fmac_f32_e32 v155, v140, v12
	v_fmac_f32_e32 v156, v140, v16
	v_fmac_f32_e32 v157, v140, v20
	v_fmac_f32_e32 v158, v140, v24
	v_fmac_f32_e32 v159, v140, v28
	v_fmac_f32_e32 v160, v140, v32
	v_fmac_f32_e32 v161, v140, v36
	v_fmac_f32_e32 v162, v140, v40
	v_fmac_f32_e32 v163, v140, v72
	v_fmac_f32_e32 v164, v140, v76
	v_fmac_f32_e32 v165, v140, v80
	v_fmac_f32_e32 v166, v140, v84
	v_fmac_f32_e32 v167, v140, v88
	v_fmac_f32_e32 v168, v140, v92
	v_fmac_f32_e32 v169, v140, v96
	v_fmac_f32_e32 v170, v140, v100
	v_fmac_f32_e32 v171, v140, v104
	v_fmac_f32_e32 v172, v140, v108
	v_fmac_f32_e32 v173, v140, v112
	v_fmac_f32_e32 v174, v140, v116
	v_fmac_f32_e32 v175, v140, v120
	v_fmac_f32_e32 v176, v140, v124
	v_fmac_f32_e32 v177, v140, v190
	v_fmac_f32_e32 v178, v140, v186
	v_fmac_f32_e32 v179, v140, v182
	v_fmac_f32_e32 v148, v128, v53
	v_fmac_f32_e32 v149, v128, v57
	v_fmac_f32_e32 v150, v128, v61
	v_fmac_f32_e32 v151, v128, v65
	v_fmac_f32_e32 v152, v128, v69
	v_fmac_f32_e32 v153, v128, v5
	v_fmac_f32_e32 v154, v128, v9
	v_fmac_f32_e32 v155, v128, v13
	v_fmac_f32_e32 v156, v128, v17
	v_fmac_f32_e32 v157, v128, v21
	v_fmac_f32_e32 v158, v128, v25
	v_fmac_f32_e32 v159, v128, v29
	v_fmac_f32_e32 v160, v128, v33
	v_fmac_f32_e32 v161, v128, v37
	v_fmac_f32_e32 v162, v128, v41
	v_fmac_f32_e32 v163, v128, v73
	v_fmac_f32_e32 v164, v128, v77
	v_fmac_f32_e32 v165, v128, v81
	v_fmac_f32_e32 v166, v128, v85
	v_fmac_f32_e32 v167, v128, v89
	v_fmac_f32_e32 v168, v128, v93
	v_fmac_f32_e32 v169, v128, v97
	v_fmac_f32_e32 v170, v128, v101
	v_fmac_f32_e32 v171, v128, v105
	v_fmac_f32_e32 v172, v128, v109
	v_fmac_f32_e32 v173, v128, v113
	v_fmac_f32_e32 v174, v128, v117
	v_fmac_f32_e32 v175, v128, v121
	v_fmac_f32_e32 v176, v128, v125
	v_fmac_f32_e32 v177, v128, v191
	v_fmac_f32_e32 v178, v128, v187
	v_fmac_f32_e32 v179, v128, v183
	ds_write2st64_b32 v138, v139, v147 offset0:144 offset1:145
	ds_write2st64_b32 v138, v148, v149 offset0:146 offset1:147
	ds_write2st64_b32 v138, v150, v151 offset0:148 offset1:149
	ds_write2st64_b32 v138, v152, v153 offset0:150 offset1:151
	ds_write2st64_b32 v138, v154, v155 offset0:152 offset1:153
	ds_write2st64_b32 v138, v156, v157 offset0:154 offset1:155
	ds_write2st64_b32 v138, v158, v159 offset0:156 offset1:157
	ds_write2st64_b32 v138, v160, v161 offset0:158 offset1:159
	ds_write2st64_b32 v138, v162, v163 offset0:160 offset1:161
	ds_write2st64_b32 v138, v164, v165 offset0:162 offset1:163
	ds_write2st64_b32 v138, v166, v167 offset0:164 offset1:165
	ds_write2st64_b32 v138, v168, v169 offset0:166 offset1:167
	ds_write2st64_b32 v138, v170, v171 offset0:168 offset1:169
	ds_write2st64_b32 v138, v172, v173 offset0:170 offset1:171
	ds_write2st64_b32 v138, v174, v175 offset0:172 offset1:173
	ds_write2st64_b32 v138, v176, v177 offset0:174 offset1:175
	ds_write2st64_b32 v138, v178, v179 offset0:176 offset1:177
	s_waitcnt lgkmcnt(0)
	s_barrier
	s_and_saveexec_b64 s[8:9], s[4:5]
	s_cbranch_execz .LBB0_138
	s_mul_i32 s7, s14, 0xc00
	v_or_b32_e32 v2, s6, v126
	v_add_u32_e32 v4, s7, v2
	v_readlane_b32 s36, v241, 18
	s_cmp_eq_u32 s12, 0
	v_ashrrev_i32_e32 v5, 31, v4
	v_ashrrev_i32_e32 v3, 31, v2
	v_readlane_b32 s42, v241, 24
	v_readlane_b32 s43, v241, 25
	s_cselect_b64 s[12:13], -1, 0
	s_mul_hi_i32 s15, s14, 34
	s_mul_i32 s14, s14, 34
	v_lshl_add_u64 v[2:3], v[2:3], 2, s[90:91]
	v_lshl_add_u64 v[4:5], v[4:5], 2, s[42:43]
	s_mov_b64 s[6:7], 0
	v_mov_b32_e32 v8, v1
	v_readlane_b32 s37, v241, 19
	v_readlane_b32 s38, v241, 20
	v_readlane_b32 s39, v241, 21
	v_readlane_b32 s40, v241, 22
	v_readlane_b32 s41, v241, 23
	v_readlane_b32 s44, v241, 26
	v_readlane_b32 s45, v241, 27
	v_readlane_b32 s46, v241, 28
	v_readlane_b32 s47, v241, 29
	v_readlane_b32 s48, v241, 30
	v_readlane_b32 s49, v241, 31
	v_readlane_b32 s50, v241, 32
	v_readlane_b32 s51, v241, 33
	s_branch .LBB0_142
